# MoBA sel/own sub-step loops: 3 fewer VALU per sub-step (row-max head as one v_max3, add-zero folded)
# baseline (speedup 1.0000x reference)
; #define LAS __attribute__((address_space(3)))
; DI float xhalf(float v) { return __shfl_xor(v, 32); }
; DI f32x16 mfma32(bf16x8 a, bf16x8 b, f32x16 c) { return __builtin_amdgcn_mfma_f32_32x32x16_bf16(a, b, c, 0, 0, 0); }
; DI bf16x8 vfrag(LAS unsigned char* p) { const s16x4 lo = tr_read(p), hi = tr_read(p + 512); return __builtin_shufflevector(lo, hi, 0, 1, 2, 3, 4, 5, 6, 7); }
; DI float fexp2(float x) { return __builtin_amdgcn_exp2f(x); }
; DI void moba_tile(const unsigned char* lds, LAS unsigned char* lds3, const bf16x8 (&qf)[4], int nsub, int diag_sub, int lane, f32x16 (&o)[2], float& m, float& l) {
;     ...
;     for (int kk = 0; kk < nsub; ++kk) {
;         bf16x8 kf[4], vf[4];
; #pragma unroll
;         for (int c = 0; c < 4; ++c) kf[c] = *(const bf16x8*)(lds + MB_K + (32 * kk + r32) * 144 + (16 * c + 8 * hi) * 2);
; #pragma unroll
;         for (int dt = 0; dt < 2; ++dt) { LAS unsigned char* vb = lds3 + MB_V + dt * 16384 + (32 * kk) * 64 + vlane; vf[2 * dt] = vfrag(vb); vf[2 * dt + 1] = vfrag(vb + 1024); }
;         f32x16 s;
; #pragma unroll
;         for (int i = 0; i < 16; ++i) s[i] = 0.f;
; #pragma unroll
;         for (int c = 0; c < 4; ++c) s = mfma32(kf[c], qf[c], s);
;         if (kk == diag_sub) {
;             const int dq = r32 - 4 * hi;
; #pragma unroll
;             for (int i = 0; i < 16; ++i) s[i] = (((i & 3) + 8 * (i >> 2)) > dq) ? -INFINITY : s[i];
;         }
;         float mx = fmaxf(fmaxf(s[0], s[1]), s[2]);
; #pragma unroll
;         for (int i = 3; i < 15; i += 2) mx = fmaxf(fmaxf(mx, s[i]), s[i + 1]);
;         mx = fmaxf(mx, s[15]);
;         mx = fmaxf(mx, xhalf(mx)) * SCL2;
;         const bool trig = mx > m + 8.f;
;         if (__any(trig)) {
;             const float mn = trig ? mx : m, al = fexp2(m - mn); l *= al; m = mn;
; #pragma unroll
;             for (int dt = 0; dt < 2; ++dt)
; #pragma unroll
;                 for (int i = 0; i < 16; ++i) o[dt][i] *= al;
;         }
;         float sum = 0.f;
; #pragma unroll
;         for (int i = 0; i < 16; ++i) { s[i] = fexp2(__builtin_fmaf(s[i], SCL2, -m)); sum += s[i]; }
;         l += sum;
;         const bf16x8 p0 = packP<0>(s), p1 = packP<1>(s);
; #pragma unroll
;         for (int dt = 0; dt < 2; ++dt) { o[dt] = mfma32(vf[2 * dt], p0, o[dt]); o[dt] = mfma32(vf[2 * dt + 1], p1, o[dt]); }
;     }
.LBB0_1308:
	v_fma_f32 v0, v34, s50, -v124
	v_exp_f32_e32 v0, v0
	v_fma_f32 v34, v35, s50, -v124
	v_exp_f32_e32 v34, v34
	v_fma_f32 v35, v36, s50, -v124
	v_exp_f32_e32 v35, v35
	v_add_f32_e32 v36, v34, v0
	v_cvt_pk_bf16_f32 v34, v0, v34
	v_add_f32_e32 v149, v35, v36
	v_fma_f32 v36, v37, s50, -v124
	v_exp_f32_e32 v150, v36
	v_fma_f32 v36, v38, s50, -v124
	v_exp_f32_e32 v151, v36
	v_fma_f32 v36, v39, s50, -v124
	v_exp_f32_e32 v152, v36
	v_fma_f32 v36, v40, s50, -v124
	v_exp_f32_e32 v153, v36
	v_fma_f32 v36, v41, s50, -v124
	v_exp_f32_e32 v154, v36
	v_fma_f32 v36, v42, s50, -v124
	v_exp_f32_e32 v42, v36
	v_fma_f32 v36, v43, s50, -v124
	v_exp_f32_e32 v43, v36
	v_fma_f32 v36, v44, s50, -v124
	v_exp_f32_e32 v44, v36
	v_fma_f32 v36, v45, s50, -v124
	v_exp_f32_e32 v45, v36
	v_fma_f32 v36, v46, s50, -v124
	v_exp_f32_e32 v46, v36
	v_fma_f32 v36, v47, s50, -v124
	v_exp_f32_e32 v47, v36
	v_cvt_pk_bf16_f32 v35, v35, v150
	v_cvt_pk_bf16_f32 v36, v151, v152
	v_cvt_pk_bf16_f32 v37, v153, v154
	v_fma_f32 v38, v48, s50, -v124
	v_exp_f32_e32 v0, v38
	v_mfma_f32_32x32x16_bf16 v[2:17], v[94:97], v[34:37], v[2:17]
	v_fma_f32 v38, v49, s50, -v124
	v_add_f32_e32 v49, v150, v149
	v_exp_f32_e32 v48, v38
	v_add_f32_e32 v49, v151, v49
	v_add_f32_e32 v49, v152, v49
	v_add_f32_e32 v49, v153, v49
	v_add_f32_e32 v49, v154, v49
	s_waitcnt lgkmcnt(2)
	v_mfma_f32_32x32x16_bf16 v[18:33], v[86:89], v[34:37], v[18:33]
	v_cvt_pk_bf16_f32 v38, v42, v43
	v_cvt_pk_bf16_f32 v39, v44, v45
	v_cvt_pk_bf16_f32 v40, v46, v47
	v_cvt_pk_bf16_f32 v41, v0, v48
	v_add_f32_e32 v42, v42, v49
	v_add_f32_e32 v42, v43, v42
	v_add_f32_e32 v34, v44, v42
	v_mfma_f32_32x32x16_bf16 v[2:17], v[90:93], v[38:41], v[2:17]
	v_add_f32_e32 v34, v45, v34
	v_add_f32_e32 v34, v46, v34
	v_add_f32_e32 v34, v47, v34
	v_add_f32_e32 v0, v0, v34
	v_add_f32_e32 v0, v48, v0
	s_add_i32 s30, s30, -1
	v_add_f32_e32 v125, v125, v0
	s_waitcnt lgkmcnt(0)
	v_mfma_f32_32x32x16_bf16 v[18:33], v[82:85], v[38:41], v[18:33]
	v_add_u32_e32 v148, 0x800, v148
	s_cmp_lg_u32 s30, 0
	v_add_u32_e32 v147, 0x1200, v147
	s_cbranch_scc0 .LBB0_1311
.LBB0_1309:
	s_waitcnt lgkmcnt(0)
	v_mfma_f32_32x32x16_bf16 v[34:49], v[192:195], v[78:81], 0
	v_mfma_f32_32x32x16_bf16 v[34:49], v[196:199], v[74:77], v[34:49]
	v_mfma_f32_32x32x16_bf16 v[34:49], v[200:203], v[70:73], v[34:49]
	v_mfma_f32_32x32x16_bf16 v[34:49], v[204:207], v[66:69], v[34:49]
	v_add_u32_e32 v0, v147, v129
	ds_read_b128 v[192:195], v0 offset:4608
	ds_read_b128 v[196:199], v0 offset:4640
	ds_read_b128 v[200:203], v0 offset:4672
	ds_read_b128 v[204:207], v0 offset:4704
	v_add_u32_e32 v0, v148, v129
	ds_read_b64_tr_b16 v[94:95], v0 offset:36864
	ds_read_b64_tr_b16 v[96:97], v0 offset:37376
	ds_read_b64_tr_b16 v[90:91], v0 offset:37888
	ds_read_b64_tr_b16 v[92:93], v0 offset:38400
	s_nop 2
	v_max3_f32 v82, v34, v35, v36
	v_max_f32_e32 v82, v82, v37
	v_max3_f32 v82, v82, v38, v39
	v_max3_f32 v82, v82, v40, v41
	v_max3_f32 v82, v82, v42, v43
	v_max3_f32 v82, v82, v44, v45
	v_max3_f32 v82, v82, v46, v47
	v_max3_f32 v149, v82, v48, v49
	v_mov_b32_e32 v150, v149
	ds_read_b64_tr_b16 v[86:87], v0 offset:53248
	ds_read_b64_tr_b16 v[88:89], v0 offset:53760
	ds_read_b64_tr_b16 v[82:83], v0 offset:54272
	ds_read_b64_tr_b16 v[84:85], v0 offset:54784
	s_waitcnt lgkmcnt(4)
	v_permlane32_swap_b32_e32 v149, v150
	v_max_f32_e32 v0, v149, v150
	v_mul_f32_e32 v0, 0x3e38aa3b, v0
	v_add_f32_e32 v149, 0x41000000, v124
	v_cmp_gt_f32_e32 vcc, v0, v149
	s_cbranch_vccz .LBB0_1308
	s_nop 0
	v_cndmask_b32_e32 v149, v124, v0, vcc
	v_sub_f32_e32 v0, v124, v149
	v_exp_f32_e32 v0, v0
	v_mov_b32_e32 v124, v149
	v_mul_f32_e32 v125, v125, v0
	v_pk_mul_f32 v[32:33], v[32:33], v[0:1] op_sel_hi:[1,0]
	v_pk_mul_f32 v[30:31], v[30:31], v[0:1] op_sel_hi:[1,0]
	v_pk_mul_f32 v[28:29], v[28:29], v[0:1] op_sel_hi:[1,0]
	v_pk_mul_f32 v[26:27], v[26:27], v[0:1] op_sel_hi:[1,0]
	v_pk_mul_f32 v[24:25], v[24:25], v[0:1] op_sel_hi:[1,0]
	v_pk_mul_f32 v[22:23], v[22:23], v[0:1] op_sel_hi:[1,0]
	v_pk_mul_f32 v[20:21], v[20:21], v[0:1] op_sel_hi:[1,0]
	v_pk_mul_f32 v[18:19], v[18:19], v[0:1] op_sel_hi:[1,0]
	v_pk_mul_f32 v[16:17], v[16:17], v[0:1] op_sel_hi:[1,0]
	v_pk_mul_f32 v[14:15], v[14:15], v[0:1] op_sel_hi:[1,0]
	v_pk_mul_f32 v[12:13], v[12:13], v[0:1] op_sel_hi:[1,0]
	v_pk_mul_f32 v[10:11], v[10:11], v[0:1] op_sel_hi:[1,0]
	v_pk_mul_f32 v[8:9], v[8:9], v[0:1] op_sel_hi:[1,0]
	v_pk_mul_f32 v[6:7], v[6:7], v[0:1] op_sel_hi:[1,0]
	v_pk_mul_f32 v[4:5], v[4:5], v[0:1] op_sel_hi:[1,0]
	v_pk_mul_f32 v[2:3], v[2:3], v[0:1] op_sel_hi:[1,0]
	s_branch .LBB0_1308

; #define LAS __attribute__((address_space(3)))
; DI float xhalf(float v) { return __shfl_xor(v, 32); }
; DI f32x16 mfma32(bf16x8 a, bf16x8 b, f32x16 c) { return __builtin_amdgcn_mfma_f32_32x32x16_bf16(a, b, c, 0, 0, 0); }
; DI bf16x8 vfrag(LAS unsigned char* p) { const s16x4 lo = tr_read(p), hi = tr_read(p + 512); return __builtin_shufflevector(lo, hi, 0, 1, 2, 3, 4, 5, 6, 7); }
; DI float fexp2(float x) { return __builtin_amdgcn_exp2f(x); }
; DI void moba_tile(const unsigned char* lds, LAS unsigned char* lds3, const bf16x8 (&qf)[4], int nsub, int diag_sub, int lane, f32x16 (&o)[2], float& m, float& l) {
;     ...
;     for (int kk = 0; kk < nsub; ++kk) {
;         bf16x8 kf[4], vf[4];
; #pragma unroll
;         for (int c = 0; c < 4; ++c) kf[c] = *(const bf16x8*)(lds + MB_K + (32 * kk + r32) * 144 + (16 * c + 8 * hi) * 2);
; #pragma unroll
;         for (int dt = 0; dt < 2; ++dt) { LAS unsigned char* vb = lds3 + MB_V + dt * 16384 + (32 * kk) * 64 + vlane; vf[2 * dt] = vfrag(vb); vf[2 * dt + 1] = vfrag(vb + 1024); }
;         f32x16 s;
; #pragma unroll
;         for (int i = 0; i < 16; ++i) s[i] = 0.f;
; #pragma unroll
;         for (int c = 0; c < 4; ++c) s = mfma32(kf[c], qf[c], s);
;         if (kk == diag_sub) {
;             const int dq = r32 - 4 * hi;
; #pragma unroll
;             for (int i = 0; i < 16; ++i) s[i] = (((i & 3) + 8 * (i >> 2)) > dq) ? -INFINITY : s[i];
;         }
;         float mx = fmaxf(fmaxf(s[0], s[1]), s[2]);
; #pragma unroll
;         for (int i = 3; i < 15; i += 2) mx = fmaxf(fmaxf(mx, s[i]), s[i + 1]);
;         mx = fmaxf(mx, s[15]);
;         mx = fmaxf(mx, xhalf(mx)) * SCL2;
;         const bool trig = mx > m + 8.f;
;         if (__any(trig)) {
;             const float mn = trig ? mx : m, al = fexp2(m - mn); l *= al; m = mn;
; #pragma unroll
;             for (int dt = 0; dt < 2; ++dt)
; #pragma unroll
;                 for (int i = 0; i < 16; ++i) o[dt][i] *= al;
;         }
;         float sum = 0.f;
; #pragma unroll
;         for (int i = 0; i < 16; ++i) { s[i] = fexp2(__builtin_fmaf(s[i], SCL2, -m)); sum += s[i]; }
;         l += sum;
;         const bf16x8 p0 = packP<0>(s), p1 = packP<1>(s);
; #pragma unroll
;         for (int dt = 0; dt < 2; ++dt) { o[dt] = mfma32(vf[2 * dt], p0, o[dt]); o[dt] = mfma32(vf[2 * dt + 1], p1, o[dt]); }
;     }
.LBB0_1377:
	v_fma_f32 v0, v34, s77, -v170
	v_exp_f32_e32 v0, v0
	v_fma_f32 v34, v35, s77, -v170
	v_exp_f32_e32 v34, v34
	v_fma_f32 v35, v36, s77, -v170
	v_exp_f32_e32 v35, v35
	v_add_f32_e32 v36, v34, v0
	v_cvt_pk_bf16_f32 v34, v0, v34
	v_add_f32_e32 v174, v35, v36
	v_fma_f32 v36, v37, s77, -v170
	v_exp_f32_e32 v175, v36
	v_fma_f32 v36, v38, s77, -v170
	v_exp_f32_e32 v176, v36
	v_fma_f32 v36, v39, s77, -v170
	v_exp_f32_e32 v177, v36
	v_fma_f32 v36, v40, s77, -v170
	v_exp_f32_e32 v178, v36
	v_fma_f32 v36, v41, s77, -v170
	v_exp_f32_e32 v179, v36
	v_fma_f32 v36, v42, s77, -v170
	v_exp_f32_e32 v42, v36
	v_fma_f32 v36, v43, s77, -v170
	v_exp_f32_e32 v43, v36
	v_fma_f32 v36, v44, s77, -v170
	v_exp_f32_e32 v44, v36
	v_fma_f32 v36, v45, s77, -v170
	v_exp_f32_e32 v45, v36
	v_fma_f32 v36, v46, s77, -v170
	v_exp_f32_e32 v46, v36
	v_fma_f32 v36, v47, s77, -v170
	v_exp_f32_e32 v47, v36
	v_cvt_pk_bf16_f32 v35, v35, v175
	v_cvt_pk_bf16_f32 v36, v176, v177
	v_cvt_pk_bf16_f32 v37, v178, v179
	v_fma_f32 v38, v48, s77, -v170
	v_exp_f32_e32 v0, v38
	v_mfma_f32_32x32x16_bf16 v[2:17], v[130:133], v[34:37], v[2:17]
	v_fma_f32 v38, v49, s77, -v170
	v_add_f32_e32 v49, v175, v174
	v_exp_f32_e32 v48, v38
	v_add_f32_e32 v49, v176, v49
	v_add_f32_e32 v49, v177, v49
	v_add_f32_e32 v49, v178, v49
	v_add_f32_e32 v49, v179, v49
	s_waitcnt lgkmcnt(2)
	v_mfma_f32_32x32x16_bf16 v[18:33], v[122:125], v[34:37], v[18:33]
	v_cvt_pk_bf16_f32 v38, v42, v43
	v_cvt_pk_bf16_f32 v39, v44, v45
	v_cvt_pk_bf16_f32 v40, v46, v47
	v_cvt_pk_bf16_f32 v41, v0, v48
	v_add_f32_e32 v42, v42, v49
	v_add_f32_e32 v42, v43, v42
	v_add_f32_e32 v34, v44, v42
	v_mfma_f32_32x32x16_bf16 v[2:17], v[126:129], v[38:41], v[2:17]
	v_add_f32_e32 v34, v45, v34
	v_add_f32_e32 v34, v46, v34
	v_add_f32_e32 v34, v47, v34
	v_add_f32_e32 v0, v0, v34
	v_add_f32_e32 v0, v48, v0
	s_add_i32 s60, s60, -1
	v_add_f32_e32 v171, v171, v0
	s_waitcnt lgkmcnt(0)
	v_mfma_f32_32x32x16_bf16 v[18:33], v[118:121], v[38:41], v[18:33]
	v_add_u32_e32 v173, 0x800, v173
	s_cmp_lg_u32 s60, 0
	v_add_u32_e32 v172, 0x1200, v172
	s_cbranch_scc0 .LBB0_1381
.LBB0_1378:
	s_waitcnt vmcnt(15) lgkmcnt(0)
	v_mfma_f32_32x32x16_bf16 v[34:49], v[192:195], v[114:117], 0
	v_mfma_f32_32x32x16_bf16 v[34:49], v[196:199], v[110:113], v[34:49]
	v_mfma_f32_32x32x16_bf16 v[34:49], v[200:203], v[106:109], v[34:49]
	v_mfma_f32_32x32x16_bf16 v[34:49], v[204:207], v[102:105], v[34:49]
	v_add_u32_e32 v0, s67, v172
	ds_read_b128 v[192:195], v0 offset:4608
	ds_read_b128 v[196:199], v0 offset:4640
	ds_read_b128 v[200:203], v0 offset:4672
	ds_read_b128 v[204:207], v0 offset:4704
	v_add_u32_e32 v0, s67, v173
	ds_read_b64_tr_b16 v[130:131], v0 offset:36864
	ds_read_b64_tr_b16 v[132:133], v0 offset:37376
	ds_read_b64_tr_b16 v[126:127], v0 offset:37888
	ds_read_b64_tr_b16 v[128:129], v0 offset:38400
	s_nop 2
	v_max3_f32 v118, v34, v35, v36
	v_max_f32_e32 v118, v118, v37
	v_max3_f32 v118, v118, v38, v39
	v_max3_f32 v118, v118, v40, v41
	v_max3_f32 v118, v118, v42, v43
	v_max3_f32 v118, v118, v44, v45
	v_max3_f32 v118, v118, v46, v47
	v_max3_f32 v174, v118, v48, v49
	v_mov_b32_e32 v175, v174
	ds_read_b64_tr_b16 v[122:123], v0 offset:53248
	ds_read_b64_tr_b16 v[124:125], v0 offset:53760
	ds_read_b64_tr_b16 v[118:119], v0 offset:54272
	ds_read_b64_tr_b16 v[120:121], v0 offset:54784
	s_waitcnt lgkmcnt(4)
	v_permlane32_swap_b32_e32 v174, v175
	v_max_f32_e32 v0, v174, v175
	v_mul_f32_e32 v0, 0x3e38aa3b, v0
	v_add_f32_e32 v174, 0x41000000, v170
	v_cmp_gt_f32_e32 vcc, v0, v174
	s_cbranch_vccz .LBB0_1377
	s_nop 0
	v_cndmask_b32_e32 v174, v170, v0, vcc
	v_sub_f32_e32 v0, v170, v174
	v_exp_f32_e32 v0, v0
	v_mov_b32_e32 v170, v174
	v_mul_f32_e32 v171, v171, v0
	v_pk_mul_f32 v[32:33], v[32:33], v[0:1] op_sel_hi:[1,0]
	v_pk_mul_f32 v[30:31], v[30:31], v[0:1] op_sel_hi:[1,0]
	v_pk_mul_f32 v[28:29], v[28:29], v[0:1] op_sel_hi:[1,0]
	v_pk_mul_f32 v[26:27], v[26:27], v[0:1] op_sel_hi:[1,0]
	v_pk_mul_f32 v[24:25], v[24:25], v[0:1] op_sel_hi:[1,0]
	v_pk_mul_f32 v[22:23], v[22:23], v[0:1] op_sel_hi:[1,0]
	v_pk_mul_f32 v[20:21], v[20:21], v[0:1] op_sel_hi:[1,0]
	v_pk_mul_f32 v[18:19], v[18:19], v[0:1] op_sel_hi:[1,0]
	v_pk_mul_f32 v[16:17], v[16:17], v[0:1] op_sel_hi:[1,0]
	v_pk_mul_f32 v[14:15], v[14:15], v[0:1] op_sel_hi:[1,0]
	v_pk_mul_f32 v[12:13], v[12:13], v[0:1] op_sel_hi:[1,0]
	v_pk_mul_f32 v[10:11], v[10:11], v[0:1] op_sel_hi:[1,0]
	v_pk_mul_f32 v[8:9], v[8:9], v[0:1] op_sel_hi:[1,0]
	v_pk_mul_f32 v[6:7], v[6:7], v[0:1] op_sel_hi:[1,0]
	v_pk_mul_f32 v[4:5], v[4:5], v[0:1] op_sel_hi:[1,0]
	v_pk_mul_f32 v[2:3], v[2:3], v[0:1] op_sel_hi:[1,0]
	s_branch .LBB0_1377
